# attention diff/MLA: first-tile rescale forced through the threshold register (-inf for tile 0) instead of a per-tile tile-index test; redundant lgkmcnt(0) before the tile barrier dropped
# speedup vs baseline: 1.0029x; 1.0029x over previous
.LBB0_106:
	v_mov_b32_e32 v14, v0
	v_mov_b32_e32 v15, v0
	s_waitcnt vmcnt(0) lgkmcnt(0)
	s_barrier
	v_mov_b32_e32 v1, v0
	v_mov_b32_e32 v2, v0
	v_mov_b32_e32 v3, v0
	v_mov_b32_e32 v4, v0
	v_mov_b32_e32 v5, v0
	v_mov_b32_e32 v6, v0
	v_mov_b32_e32 v7, v0
	v_mov_b32_e32 v8, v0
	v_mov_b32_e32 v9, v0
	v_mov_b32_e32 v10, v0
	v_mov_b32_e32 v11, v0
	v_mov_b32_e32 v12, v0
	v_mov_b32_e32 v13, v0
	s_lshl_b32 s30, s43, 12
	s_lshl_b32 s44, s48, 7
	v_mov_b64_e32 v[62:63], v[14:15]
	v_mov_b64_e32 v[46:47], v[14:15]
	v_mov_b64_e32 v[30:31], v[14:15]
	s_add_i32 s43, s30, 0xffffff80
	v_add_u32_e32 v153, s44, v171
	v_add_u32_e32 v155, s44, v172
	s_add_i32 s45, s46, 0x80
	s_mov_b32 s50, 2
	s_mov_b32 s51, 1
	s_mov_b32 s53, 0
	v_mov_b32_e32 v157, 0
	v_mov_b32_e32 v159, 0
	v_mov_b32_e32 v96, 0
	v_mov_b32_e32 v97, 0
	v_mov_b32_e32 v98, 0
	v_mov_b32_e32 v99, 0
	v_mov_b32_e32 v100, 0
	v_mov_b32_e32 v101, 0
	v_mov_b32_e32 v102, 0
	v_mov_b32_e32 v103, 0
	v_mov_b32_e32 v104, 0
	v_mov_b32_e32 v105, 0
	v_mov_b32_e32 v106, 0
	v_mov_b32_e32 v107, 0
	v_mov_b32_e32 v108, 0
	v_mov_b32_e32 v109, 0
	v_mov_b32_e32 v110, 0
	v_mov_b32_e32 v111, 0
	v_mov_b64_e32 v[60:61], v[12:13]
	v_mov_b64_e32 v[58:59], v[10:11]
	v_mov_b64_e32 v[56:57], v[8:9]
	v_mov_b64_e32 v[54:55], v[6:7]
	v_mov_b64_e32 v[52:53], v[4:5]
	v_mov_b64_e32 v[50:51], v[2:3]
	v_mov_b64_e32 v[48:49], v[0:1]
	v_mov_b64_e32 v[44:45], v[12:13]
	v_mov_b64_e32 v[42:43], v[10:11]
	v_mov_b64_e32 v[40:41], v[8:9]
	v_mov_b64_e32 v[38:39], v[6:7]
	v_mov_b64_e32 v[36:37], v[4:5]
	v_mov_b64_e32 v[34:35], v[2:3]
	v_mov_b64_e32 v[32:33], v[0:1]
	v_mov_b64_e32 v[28:29], v[12:13]
	v_mov_b64_e32 v[26:27], v[10:11]
	v_mov_b64_e32 v[24:25], v[8:9]
	v_mov_b64_e32 v[22:23], v[6:7]
	v_mov_b64_e32 v[20:21], v[4:5]
	v_mov_b64_e32 v[18:19], v[2:3]
	v_mov_b64_e32 v[16:17], v[0:1]
	s_mov_b32 s52, 0
	s_waitcnt vmcnt(0)
	s_mul_i32 s30, s53, 0x2400
	v_add_u32_e32 v242, s30, v173
	s_mul_i32 s30, s53, 0x4800
	v_add_u32_e32 v243, s30, v174
	s_mov_b32 s58, 0xff800000
	v_readfirstlane_b32 s30, v191
	s_lshr_b32 s30, s30, 8
	s_cmp_eq_u32 s30, 0
	s_cbranch_scc1 .Latt_diff_p0
	s_setprio 1

.Latt_diff_dmaend:
	s_waitcnt lgkmcnt(2)
	v_mfma_f32_32x32x16_bf16 v[64:79], v[112:115], v[130:133], v[96:111]
	ds_read_b128 v[112:115], v242 offset:4608
	v_mfma_f32_32x32x16_bf16 v[64:79], v[116:119], v[134:137], v[64:79]
	ds_read_b128 v[116:119], v242 offset:4640
	s_waitcnt lgkmcnt(2)
	v_mfma_f32_32x32x16_bf16 v[64:79], v[120:123], v[138:141], v[64:79]
	ds_read_b128 v[120:123], v242 offset:4672
	v_mfma_f32_32x32x16_bf16 v[64:79], v[124:127], v[142:145], v[64:79]
	ds_read_b128 v[124:127], v242 offset:4704
	s_waitcnt lgkmcnt(2)
	v_mfma_f32_32x32x16_bf16 v[80:95], v[112:115], v[130:133], v[96:111]
	v_mfma_f32_32x32x16_bf16 v[80:95], v[116:119], v[134:137], v[80:95]
	s_waitcnt lgkmcnt(0)
	v_mfma_f32_32x32x16_bf16 v[80:95], v[120:123], v[138:141], v[80:95]
	v_mfma_f32_32x32x16_bf16 v[80:95], v[124:127], v[142:145], v[80:95]
	ds_read_b128 v[112:115], v243 offset:27648
	ds_read_b128 v[116:119], v243 offset:32256
	ds_read_b128 v[120:123], v243 offset:36864
	ds_read_b128 v[124:127], v243 offset:41472
	s_nop 0
	v_max3_f32 v227, v64, v65, v66
	v_max3_f32 v228, v67, v68, v69
	v_max3_f32 v227, v227, v70, v71
	v_max3_f32 v228, v228, v72, v73
	v_max3_f32 v227, v227, v74, v75
	v_max3_f32 v228, v228, v76, v77
	v_max3_f32 v227, v227, v78, v79
	v_max3_f32 v229, v80, v81, v82
	v_max3_f32 v226, v83, v84, v85
	v_max3_f32 v229, v229, v86, v87
	v_max3_f32 v226, v226, v88, v89
	v_max3_f32 v229, v229, v90, v91
	v_max3_f32 v226, v226, v92, v93
	v_max3_f32 v229, v229, v94, v95
	v_max3_f32 v226, v226, v227, v228
	v_max_f32_e32 v226, v226, v229
	v_cmp_lt_f32_e32 vcc, s58, v226
	s_cbranch_vccnz .Latt_diff_rare

.Latt_diff_wd:
	s_add_i32 s30, s50, 1
	s_cmp_lg_u32 s50, 2
	s_cselect_b32 s46, s30, 0
	s_add_i32 s52, s52, 1
	s_add_i32 s43, s43, 64
	s_add_i32 s45, s45, 64
	s_mov_b32 s53, s51
	s_mov_b32 s51, s50
	s_mov_b32 s50, s46
	s_mul_i32 s30, s53, 0x2400
	v_add_u32_e32 v242, s30, v173
	s_mul_i32 s30, s53, 0x4800
	v_add_u32_e32 v243, s30, v174
	s_cmp_eq_u32 s21, s52
	s_barrier
	s_cbranch_scc0 .LBB0_107
	s_branch .LBB0_88

.Latt_diff_rare:
	s_cmp_eq_u32 s52, 0
	s_cselect_b32 s31, 0xff7fffff, 0
	s_mov_b32 s58, 0x41000000
	v_mov_b32_e32 v227, v226
	s_nop 1
	v_permlane32_swap_b32_e32 v226, v227
	v_max_f32_e32 v237, v226, v227
	v_max_f32_e32 v238, s31, v237
	v_max_f32_e32 v239, 0, v238
	v_add_f32_e32 v159, v159, v238
	v_exp_f32_e64 v240, -v239
	v_sub_f32_e32 v96, v96, v238
	v_mov_b32_e32 v97, v96
	v_mov_b32_e32 v98, v96
	v_mov_b32_e32 v99, v96
	v_mov_b32_e32 v100, v96
	v_mov_b32_e32 v101, v96
	v_mov_b32_e32 v102, v96
	v_mov_b32_e32 v103, v96
	v_mov_b32_e32 v104, v96
	v_mov_b32_e32 v105, v96
	v_mov_b32_e32 v106, v96
	v_mov_b32_e32 v107, v96
	v_mov_b32_e32 v108, v96
	v_mov_b32_e32 v109, v96
	v_mov_b32_e32 v110, v96
	v_mov_b32_e32 v111, v96
	v_sub_f32_e32 v64, v64, v238
	v_sub_f32_e32 v65, v65, v238
	v_sub_f32_e32 v66, v66, v238
	v_sub_f32_e32 v67, v67, v238
	v_sub_f32_e32 v68, v68, v238
	v_sub_f32_e32 v69, v69, v238
	v_sub_f32_e32 v70, v70, v238
	v_sub_f32_e32 v71, v71, v238
	v_sub_f32_e32 v72, v72, v238
	v_sub_f32_e32 v73, v73, v238
	v_sub_f32_e32 v74, v74, v238
	v_sub_f32_e32 v75, v75, v238
	v_sub_f32_e32 v76, v76, v238
	v_sub_f32_e32 v77, v77, v238
	v_sub_f32_e32 v78, v78, v238
	v_sub_f32_e32 v79, v79, v238
	v_sub_f32_e32 v80, v80, v238
	v_sub_f32_e32 v81, v81, v238
	v_sub_f32_e32 v82, v82, v238
	v_sub_f32_e32 v83, v83, v238
	v_sub_f32_e32 v84, v84, v238
	v_sub_f32_e32 v85, v85, v238
	v_sub_f32_e32 v86, v86, v238
	v_sub_f32_e32 v87, v87, v238
	v_sub_f32_e32 v88, v88, v238
	v_sub_f32_e32 v89, v89, v238
	v_sub_f32_e32 v90, v90, v238
	v_sub_f32_e32 v91, v91, v238
	v_sub_f32_e32 v92, v92, v238
	v_sub_f32_e32 v93, v93, v238
	v_sub_f32_e32 v94, v94, v238
	v_sub_f32_e32 v95, v95, v238
	v_mul_f32_e32 v157, v157, v240
	v_pk_mul_f32 v[0:1], v[0:1], v[240:241] op_sel_hi:[1,0]
	v_pk_mul_f32 v[2:3], v[2:3], v[240:241] op_sel_hi:[1,0]
	v_pk_mul_f32 v[4:5], v[4:5], v[240:241] op_sel_hi:[1,0]
	v_pk_mul_f32 v[6:7], v[6:7], v[240:241] op_sel_hi:[1,0]
	v_pk_mul_f32 v[8:9], v[8:9], v[240:241] op_sel_hi:[1,0]
	v_pk_mul_f32 v[10:11], v[10:11], v[240:241] op_sel_hi:[1,0]
	v_pk_mul_f32 v[12:13], v[12:13], v[240:241] op_sel_hi:[1,0]
	v_pk_mul_f32 v[14:15], v[14:15], v[240:241] op_sel_hi:[1,0]
	v_pk_mul_f32 v[48:49], v[48:49], v[240:241] op_sel_hi:[1,0]
	v_pk_mul_f32 v[50:51], v[50:51], v[240:241] op_sel_hi:[1,0]
	v_pk_mul_f32 v[52:53], v[52:53], v[240:241] op_sel_hi:[1,0]
	v_pk_mul_f32 v[54:55], v[54:55], v[240:241] op_sel_hi:[1,0]
	v_pk_mul_f32 v[56:57], v[56:57], v[240:241] op_sel_hi:[1,0]
	v_pk_mul_f32 v[58:59], v[58:59], v[240:241] op_sel_hi:[1,0]
	v_pk_mul_f32 v[60:61], v[60:61], v[240:241] op_sel_hi:[1,0]
	v_pk_mul_f32 v[62:63], v[62:63], v[240:241] op_sel_hi:[1,0]
	v_pk_mul_f32 v[32:33], v[32:33], v[240:241] op_sel_hi:[1,0]
	v_pk_mul_f32 v[34:35], v[34:35], v[240:241] op_sel_hi:[1,0]
	v_pk_mul_f32 v[36:37], v[36:37], v[240:241] op_sel_hi:[1,0]
	v_pk_mul_f32 v[38:39], v[38:39], v[240:241] op_sel_hi:[1,0]
	v_pk_mul_f32 v[40:41], v[40:41], v[240:241] op_sel_hi:[1,0]
	v_pk_mul_f32 v[42:43], v[42:43], v[240:241] op_sel_hi:[1,0]
	v_pk_mul_f32 v[44:45], v[44:45], v[240:241] op_sel_hi:[1,0]
	v_pk_mul_f32 v[46:47], v[46:47], v[240:241] op_sel_hi:[1,0]
	v_pk_mul_f32 v[16:17], v[16:17], v[240:241] op_sel_hi:[1,0]
	v_pk_mul_f32 v[18:19], v[18:19], v[240:241] op_sel_hi:[1,0]
	v_pk_mul_f32 v[20:21], v[20:21], v[240:241] op_sel_hi:[1,0]
	v_pk_mul_f32 v[22:23], v[22:23], v[240:241] op_sel_hi:[1,0]
	v_pk_mul_f32 v[24:25], v[24:25], v[240:241] op_sel_hi:[1,0]
	v_pk_mul_f32 v[26:27], v[26:27], v[240:241] op_sel_hi:[1,0]
	v_pk_mul_f32 v[28:29], v[28:29], v[240:241] op_sel_hi:[1,0]
	v_pk_mul_f32 v[30:31], v[30:31], v[240:241] op_sel_hi:[1,0]
	s_branch .Latt_diff_norescale

.LBB0_177:
	v_mov_b32_e32 v14, v0
	v_mov_b32_e32 v15, v0
	s_waitcnt vmcnt(0) lgkmcnt(0)
	s_barrier
	v_mov_b32_e32 v1, v0
	v_mov_b32_e32 v2, v0
	v_mov_b32_e32 v3, v0
	v_mov_b32_e32 v4, v0
	v_mov_b32_e32 v5, v0
	v_mov_b32_e32 v6, v0
	v_mov_b32_e32 v7, v0
	v_mov_b32_e32 v8, v0
	v_mov_b32_e32 v9, v0
	v_mov_b32_e32 v10, v0
	v_mov_b32_e32 v11, v0
	v_mov_b32_e32 v12, v0
	v_mov_b32_e32 v13, v0
	s_lshl_b32 s49, s49, 12
	v_mov_b64_e32 v[30:31], v[14:15]
	v_mov_b64_e32 v[46:47], v[14:15]
	v_mov_b64_e32 v[62:63], v[14:15]
	v_mad_u64_u32 v[222:223], s[30:31], s50, v238, v[190:191]
	v_mad_u64_u32 v[224:225], s[30:31], s50, v240, v[192:193]
	v_mad_u64_u32 v[226:227], s[30:31], s50, v242, v[194:195]
	v_mad_u64_u32 v[228:229], s[30:31], s50, v244, v[196:197]
	s_addk_i32 s49, 0xff80
	s_add_i32 s51, s60, 0x80
	s_mov_b32 s52, 2
	s_mov_b32 s53, 1
	s_mov_b32 s56, 0
	v_mov_b32_e32 v205, 0
	v_mov_b32_e32 v207, 0
	v_mov_b32_e32 v96, 0
	v_mov_b32_e32 v97, 0
	v_mov_b32_e32 v98, 0
	v_mov_b32_e32 v99, 0
	v_mov_b32_e32 v100, 0
	v_mov_b32_e32 v101, 0
	v_mov_b32_e32 v102, 0
	v_mov_b32_e32 v103, 0
	v_mov_b32_e32 v104, 0
	v_mov_b32_e32 v105, 0
	v_mov_b32_e32 v106, 0
	v_mov_b32_e32 v107, 0
	v_mov_b32_e32 v108, 0
	v_mov_b32_e32 v109, 0
	v_mov_b32_e32 v110, 0
	v_mov_b32_e32 v111, 0
	v_mov_b64_e32 v[28:29], v[12:13]
	v_mov_b64_e32 v[26:27], v[10:11]
	v_mov_b64_e32 v[24:25], v[8:9]
	v_mov_b64_e32 v[22:23], v[6:7]
	v_mov_b64_e32 v[20:21], v[4:5]
	v_mov_b64_e32 v[18:19], v[2:3]
	v_mov_b64_e32 v[16:17], v[0:1]
	v_mov_b64_e32 v[44:45], v[12:13]
	v_mov_b64_e32 v[42:43], v[10:11]
	v_mov_b64_e32 v[40:41], v[8:9]
	v_mov_b64_e32 v[38:39], v[6:7]
	v_mov_b64_e32 v[36:37], v[4:5]
	v_mov_b64_e32 v[34:35], v[2:3]
	v_mov_b64_e32 v[32:33], v[0:1]
	v_mov_b64_e32 v[60:61], v[12:13]
	v_mov_b64_e32 v[58:59], v[10:11]
	v_mov_b64_e32 v[56:57], v[8:9]
	v_mov_b64_e32 v[54:55], v[6:7]
	v_mov_b64_e32 v[52:53], v[4:5]
	v_mov_b64_e32 v[50:51], v[2:3]
	v_mov_b64_e32 v[48:49], v[0:1]
	s_mov_b32 s55, 0
	s_waitcnt vmcnt(0)
	s_mul_i32 s30, s56, 0x6400
	v_add_u32_e32 v209, s30, v246
	s_mul_i32 s30, s56, 0x4800
	v_add_u32_e32 v219, s30, v247
	s_mov_b32 s58, 0xff800000
	v_readfirstlane_b32 s30, v191
	s_lshr_b32 s30, s30, 8
	s_cmp_eq_u32 s30, 0
	s_cbranch_scc1 .Latt_mla_p0
	s_setprio 1

.Latt_mla_dmaend:
	s_waitcnt lgkmcnt(3)
	v_mfma_f32_32x32x16_bf16 v[64:79], v[112:115], v[130:133], v[96:111]
	ds_read_b128 v[112:115], v209 offset:160
	v_mfma_f32_32x32x16_bf16 v[64:79], v[116:119], v[134:137], v[64:79]
	ds_read_b128 v[116:119], v209 offset:192
	s_waitcnt lgkmcnt(3)
	v_mfma_f32_32x32x16_bf16 v[64:79], v[120:123], v[138:141], v[64:79]
	ds_read_b128 v[120:123], v209 offset:224
	v_mfma_f32_32x32x16_bf16 v[64:79], v[124:127], v[142:145], v[64:79]
	ds_read_b128 v[124:127], v209 offset:256
	s_waitcnt lgkmcnt(3)
	v_mfma_f32_32x32x16_bf16 v[64:79], v[250:253], v[146:149], v[64:79]
	ds_read_b128 v[250:253], v209 offset:288
	v_mfma_f32_32x32x16_bf16 v[64:79], v[112:115], v[150:153], v[64:79]
	ds_read_b128 v[112:115], v209 offset:320
	s_waitcnt lgkmcnt(3)
	v_mfma_f32_32x32x16_bf16 v[64:79], v[116:119], v[154:157], v[64:79]
	ds_read_b128 v[116:119], v209 offset:352
	v_mfma_f32_32x32x16_bf16 v[64:79], v[120:123], v[158:161], v[64:79]
	ds_read_b128 v[120:123], v209 offset:12800
	s_waitcnt lgkmcnt(3)
	v_mfma_f32_32x32x16_bf16 v[64:79], v[124:127], v[162:165], v[64:79]
	ds_read_b128 v[124:127], v209 offset:12832
	v_mfma_f32_32x32x16_bf16 v[64:79], v[250:253], v[166:169], v[64:79]
	ds_read_b128 v[250:253], v209 offset:12864
	s_waitcnt lgkmcnt(3)
	v_mfma_f32_32x32x16_bf16 v[64:79], v[112:115], v[170:173], v[64:79]
	ds_read_b128 v[112:115], v209 offset:12896
	v_mfma_f32_32x32x16_bf16 v[64:79], v[116:119], v[174:177], v[64:79]
	ds_read_b128 v[116:119], v209 offset:12928
	s_waitcnt lgkmcnt(3)
	v_mfma_f32_32x32x16_bf16 v[80:95], v[120:123], v[130:133], v[96:111]
	ds_read_b128 v[120:123], v209 offset:12960
	v_mfma_f32_32x32x16_bf16 v[80:95], v[124:127], v[134:137], v[80:95]
	ds_read_b128 v[124:127], v209 offset:12992
	s_waitcnt lgkmcnt(3)
	v_mfma_f32_32x32x16_bf16 v[80:95], v[250:253], v[138:141], v[80:95]
	ds_read_b128 v[250:253], v209 offset:13024
	v_mfma_f32_32x32x16_bf16 v[80:95], v[112:115], v[142:145], v[80:95]
	ds_read_b128 v[112:115], v209 offset:13056
	s_waitcnt lgkmcnt(3)
	v_mfma_f32_32x32x16_bf16 v[80:95], v[116:119], v[146:149], v[80:95]
	ds_read_b128 v[116:119], v209 offset:13088
	v_max3_f32 v211, v64, v65, v66
	v_mfma_f32_32x32x16_bf16 v[80:95], v[120:123], v[150:153], v[80:95]
	ds_read_b128 v[120:123], v209 offset:13120
	v_max3_f32 v213, v67, v68, v69
	s_waitcnt lgkmcnt(3)
	v_mfma_f32_32x32x16_bf16 v[80:95], v[124:127], v[154:157], v[80:95]
	ds_read_b128 v[124:127], v209 offset:13152
	v_max3_f32 v211, v211, v70, v71
	v_mfma_f32_32x32x16_bf16 v[80:95], v[250:253], v[158:161], v[80:95]
	v_max3_f32 v213, v213, v72, v73
	s_waitcnt lgkmcnt(2)
	v_mfma_f32_32x32x16_bf16 v[80:95], v[112:115], v[162:165], v[80:95]
	v_max3_f32 v211, v211, v74, v75
	v_mfma_f32_32x32x16_bf16 v[80:95], v[116:119], v[166:169], v[80:95]
	v_max3_f32 v213, v213, v76, v77
	s_waitcnt lgkmcnt(0)
	v_mfma_f32_32x32x16_bf16 v[80:95], v[120:123], v[170:173], v[80:95]
	v_max3_f32 v211, v211, v78, v79
	v_mfma_f32_32x32x16_bf16 v[80:95], v[124:127], v[174:177], v[80:95]
	ds_read_b128 v[112:115], v219 offset:0
	ds_read_b128 v[116:119], v219 offset:4608
	ds_read_b128 v[120:123], v219 offset:9216
	s_nop 8
	v_max3_f32 v215, v80, v81, v82
	v_max3_f32 v209, v83, v84, v85
	v_max3_f32 v215, v215, v86, v87
	v_max3_f32 v209, v209, v88, v89
	v_max3_f32 v215, v215, v90, v91
	v_max3_f32 v209, v209, v92, v93
	v_max3_f32 v215, v215, v94, v95
	v_max3_f32 v209, v209, v211, v213
	v_max_f32_e32 v209, v209, v215
	v_cmp_lt_f32_e32 vcc, s58, v209
	s_cbranch_vccnz .Latt_mla_rare

.Latt_mla_wd:
	s_add_i32 s30, s52, 1
	s_cmp_lg_u32 s52, 2
	s_cselect_b32 s57, s30, 0
	s_add_i32 s55, s55, 1
	s_add_i32 s49, s49, 64
	s_add_i32 s51, s51, 64
	s_mov_b32 s56, s53
	s_mov_b32 s53, s52
	s_mov_b32 s52, s57
	s_mul_i32 s30, s56, 0x6400
	v_add_u32_e32 v209, s30, v246
	s_mul_i32 s30, s56, 0x4800
	v_add_u32_e32 v219, s30, v247
	s_cmp_eq_u32 s20, s55
	s_barrier
	s_cbranch_scc0 .LBB0_178
	s_branch .LBB0_153

.Latt_mla_rare:
	s_cmp_eq_u32 s55, 0
	s_cselect_b32 s31, 0xff7fffff, 0
	s_mov_b32 s58, 0x41000000
	v_mov_b32_e32 v211, v209
	s_nop 1
	v_permlane32_swap_b32_e32 v209, v211
	v_max_f32_e32 v217, v209, v211
	v_max_f32_e32 v211, s31, v217
	v_max_f32_e32 v213, 0, v211
	v_add_f32_e32 v207, v207, v211
	v_exp_f32_e64 v250, -v213
	v_sub_f32_e32 v96, v96, v211
	v_mov_b32_e32 v97, v96
	v_mov_b32_e32 v98, v96
	v_mov_b32_e32 v99, v96
	v_mov_b32_e32 v100, v96
	v_mov_b32_e32 v101, v96
	v_mov_b32_e32 v102, v96
	v_mov_b32_e32 v103, v96
	v_mov_b32_e32 v104, v96
	v_mov_b32_e32 v105, v96
	v_mov_b32_e32 v106, v96
	v_mov_b32_e32 v107, v96
	v_mov_b32_e32 v108, v96
	v_mov_b32_e32 v109, v96
	v_mov_b32_e32 v110, v96
	v_mov_b32_e32 v111, v96
	v_sub_f32_e32 v64, v64, v211
	v_sub_f32_e32 v65, v65, v211
	v_sub_f32_e32 v66, v66, v211
	v_sub_f32_e32 v67, v67, v211
	v_sub_f32_e32 v68, v68, v211
	v_sub_f32_e32 v69, v69, v211
	v_sub_f32_e32 v70, v70, v211
	v_sub_f32_e32 v71, v71, v211
	v_sub_f32_e32 v72, v72, v211
	v_sub_f32_e32 v73, v73, v211
	v_sub_f32_e32 v74, v74, v211
	v_sub_f32_e32 v75, v75, v211
	v_sub_f32_e32 v76, v76, v211
	v_sub_f32_e32 v77, v77, v211
	v_sub_f32_e32 v78, v78, v211
	v_sub_f32_e32 v79, v79, v211
	v_sub_f32_e32 v80, v80, v211
	v_sub_f32_e32 v81, v81, v211
	v_sub_f32_e32 v82, v82, v211
	v_sub_f32_e32 v83, v83, v211
	v_sub_f32_e32 v84, v84, v211
	v_sub_f32_e32 v85, v85, v211
	v_sub_f32_e32 v86, v86, v211
	v_sub_f32_e32 v87, v87, v211
	v_sub_f32_e32 v88, v88, v211
	v_sub_f32_e32 v89, v89, v211
	v_sub_f32_e32 v90, v90, v211
	v_sub_f32_e32 v91, v91, v211
	v_sub_f32_e32 v92, v92, v211
	v_sub_f32_e32 v93, v93, v211
	v_sub_f32_e32 v94, v94, v211
	v_sub_f32_e32 v95, v95, v211
	v_mul_f32_e32 v205, v205, v250
	v_pk_mul_f32 v[48:49], v[48:49], v[250:251] op_sel_hi:[1,0]
	v_pk_mul_f32 v[50:51], v[50:51], v[250:251] op_sel_hi:[1,0]
	v_pk_mul_f32 v[52:53], v[52:53], v[250:251] op_sel_hi:[1,0]
	v_pk_mul_f32 v[54:55], v[54:55], v[250:251] op_sel_hi:[1,0]
	v_pk_mul_f32 v[56:57], v[56:57], v[250:251] op_sel_hi:[1,0]
	v_pk_mul_f32 v[58:59], v[58:59], v[250:251] op_sel_hi:[1,0]
	v_pk_mul_f32 v[60:61], v[60:61], v[250:251] op_sel_hi:[1,0]
	v_pk_mul_f32 v[62:63], v[62:63], v[250:251] op_sel_hi:[1,0]
	v_pk_mul_f32 v[32:33], v[32:33], v[250:251] op_sel_hi:[1,0]
	v_pk_mul_f32 v[34:35], v[34:35], v[250:251] op_sel_hi:[1,0]
	v_pk_mul_f32 v[36:37], v[36:37], v[250:251] op_sel_hi:[1,0]
	v_pk_mul_f32 v[38:39], v[38:39], v[250:251] op_sel_hi:[1,0]
	v_pk_mul_f32 v[40:41], v[40:41], v[250:251] op_sel_hi:[1,0]
	v_pk_mul_f32 v[42:43], v[42:43], v[250:251] op_sel_hi:[1,0]
	v_pk_mul_f32 v[44:45], v[44:45], v[250:251] op_sel_hi:[1,0]
	v_pk_mul_f32 v[46:47], v[46:47], v[250:251] op_sel_hi:[1,0]
	v_pk_mul_f32 v[16:17], v[16:17], v[250:251] op_sel_hi:[1,0]
	v_pk_mul_f32 v[18:19], v[18:19], v[250:251] op_sel_hi:[1,0]
	v_pk_mul_f32 v[20:21], v[20:21], v[250:251] op_sel_hi:[1,0]
	v_pk_mul_f32 v[22:23], v[22:23], v[250:251] op_sel_hi:[1,0]
	v_pk_mul_f32 v[24:25], v[24:25], v[250:251] op_sel_hi:[1,0]
	v_pk_mul_f32 v[26:27], v[26:27], v[250:251] op_sel_hi:[1,0]
	v_pk_mul_f32 v[28:29], v[28:29], v[250:251] op_sel_hi:[1,0]
	v_pk_mul_f32 v[30:31], v[30:31], v[250:251] op_sel_hi:[1,0]
	v_pk_mul_f32 v[0:1], v[0:1], v[250:251] op_sel_hi:[1,0]
	v_pk_mul_f32 v[2:3], v[2:3], v[250:251] op_sel_hi:[1,0]
	v_pk_mul_f32 v[4:5], v[4:5], v[250:251] op_sel_hi:[1,0]
	v_pk_mul_f32 v[6:7], v[6:7], v[250:251] op_sel_hi:[1,0]
	v_pk_mul_f32 v[8:9], v[8:9], v[250:251] op_sel_hi:[1,0]
	v_pk_mul_f32 v[10:11], v[10:11], v[250:251] op_sel_hi:[1,0]
	v_pk_mul_f32 v[12:13], v[12:13], v[250:251] op_sel_hi:[1,0]
	v_pk_mul_f32 v[14:15], v[14:15], v[250:251] op_sel_hi:[1,0]
	s_branch .Latt_mla_norescale
